# combo32 + attention phases: wave 0 (work-unit claimer, every unit barrier waits for it) at static priority 2 above waves 4-7 at 1
# speedup vs baseline: 1.0088x; 1.0088x over previous
; #define LAS __attribute__((address_space(3)))
; __device__ __forceinline__ void attn_phase(const AttnCtx& C, unsigned* counter, LAS unsigned char* lds, int tid) {
;     LAS unsigned* ub = (LAS unsigned*)(lds + AL_U);
;     __syncthreads();
;     if (tid == 0) ub[0] = atomicAdd(counter, 1u);
;     for (;;) {
;         __syncthreads();
;         const int u = (int)ub[0];
;         if (u >= ATT_UNITS) break;
.Lprio_lo_1:
	s_cmp_lg_u32 s82, 0
	s_cbranch_scc1 .Lprio_skip_1
	s_setprio 2
